# speedup vs baseline: 1.0099x; 1.0010x over previous
; #define PG8_STAGE(bufoff, gbase, voff) do { _Pragma("unroll") for (int _i = 0; _i < 2; ++_i) \
;         __builtin_amdgcn_global_load_lds((const unsigned*)((const char*)(gbase) + (voff)[_i]), (PG8_LAS unsigned*)(lds + (bufoff) + ldsw + _i * 8192), 16, 0, 0); } while (0)
; #define PG8_LDA(dst, b, h) do { _Pragma("unroll") for (int m = 0; m < 4; ++m) _Pragma("unroll") for (int k = 0; k < 2; ++k) dst[m][k] = *(const PG8_LAS bf16x8*)(lds + PG8_SA(b, h) + aoff + m * 2048 + k * 1024); } while (0)
; #define PG8_LDB(dst, b, h) do { _Pragma("unroll") for (int n = 0; n < 2; ++n) _Pragma("unroll") for (int k = 0; k < 2; ++k) dst[n][k] = *(const PG8_LAS bf16x8*)(lds + PG8_SB(b, h) + boff + n * 2048 + k * 1024); } while (0)
; #define PG8_BAR __builtin_amdgcn_s_barrier()
;     __host__ __device__ bool next(int i, Unit& u) const {
;         const long L = (long)i * G + c; if (L >= nwg) return false;
;         int wgid = (int)L; { const int q = nwg / NXCD, r = nwg % NXCD, xcd = wgid % NXCD, off = wgid / NXCD; wgid = (xcd < r ? xcd * (q + 1) : r * (q + 1) + (xcd - r) * q) + off; }
;         const int nig = WGM * nN, gid = wgid / nig, fm = gid * WGM, gsz = (nM - fm) < WGM ? (nM - fm) : WGM;
;         u.pm = fm + ((wgid % nig) % gsz); u.pn = (wgid % nig) / gsz; return true;
;     }
; template <class Epi, class Sched, bool ALIGN_EPI = false, bool SP2 = false>
; __device__ __forceinline__ void gemm_phase(PG8_LAS unsigned char* lds, const Gemm g, const Sched& S, const Epi& E) {
;     ...
;         const bool has_next = S.next(ui + 1, nxt);
;         const char* nA = has_next ? (const char*)g.A + (size_t)nxt.pm * tstep : cA; const char* nB = has_next ? (const char*)g.Bt + (size_t)nxt.pn * tstep : cB;
;         for (int t = 0; t < nt; t += 2) {
;             const bool last = (t == nt - 2);
;             const char* a1 = cA + (size_t)(t + 1) * kstep;
;             const char* a2 = last ? nA : cA + (size_t)(t + 2) * kstep; const char* b2 = last ? nB : cB + (size_t)(t + 2) * kstep;
;             const char* a3 = a2 + kstep; const char* b3 = b2 + kstep;
;             if (last && has_next) S.a_ready(nxt);
;             if constexpr (SP2) {
;             PG8_LDB(B0, 0, 0); PG8_LDB(B1, 0, 1); PG8_SCHED; PG8_LDA(At, 0, 0); PG8_STAGE(PG8_SA(1, 1), a1 + hstep, voffA);
;             PG8_WAIT_V(8); PG8_WAIT_L(0); PG8_BAR; PG8_MMA(0, 0, At, B0); PG8_MMA(0, 1, At, B1); PG8_BAR; PG8_SCHED;
.LBB0_202:
	s_waitcnt vmcnt(16)
	v_add_u32_e32 v204, 0x10000, v238
	ds_read_b128 v[80:83], v204
	ds_read_b128 v[88:91], v204 offset:1024
	ds_read_b128 v[104:107], v204 offset:2048
	ds_read_b128 v[108:111], v204 offset:3072
	ds_read_b128 v[128:131], v204 offset:16384
	ds_read_b128 v[132:135], v204 offset:17408
	ds_read_b128 v[152:155], v204 offset:18432
	ds_read_b128 v[156:159], v204 offset:19456
	ds_read_b128 v[160:163], v240
	ds_read_b128 v[164:167], v240 offset:1024
	ds_read_b128 v[168:171], v240 offset:2048
	ds_read_b128 v[172:175], v240 offset:3072
	ds_read_b128 v[176:179], v240 offset:4096
	ds_read_b128 v[180:183], v240 offset:5120
	ds_read_b128 v[184:187], v240 offset:6144
	ds_read_b128 v[200:203], v240 offset:7168
	s_add_i32 s81, s81, 1
	s_mul_i32 s3, s81, s86
	s_mul_hi_u32 s6, s81, s14
	s_add_i32 s6, s6, s3
	s_mul_i32 s3, s81, s14
	s_add_u32 s62, s3, s2
	s_addc_u32 s63, s6, s33
	s_waitcnt lgkmcnt(0)
	v_mov_b64_e32 v[0:1], s[98:99]
	v_cmp_ge_i64_e32 vcc, s[62:63], v[0:1]
	v_cmp_lt_i64_e64 s[6:7], s[62:63], v[0:1]
	s_cbranch_vccnz .LBB0_204
	s_ashr_i32 s3, s62, 31
	s_lshr_b32 s3, s3, 29
	s_add_i32 s3, s62, s3
	s_ashr_i32 s9, s3, 3
	s_and_b32 s3, s3, -8
	s_sub_i32 s3, s62, s3
	s_lshr_b32 s36, s3, 31
	s_add_i32 s36, s15, s36
	s_mul_i32 s3, s36, s3
	s_add_i32 s3, s3, s9
	s_ashr_i32 s9, s3, 31
	s_lshr_b32 s9, s9, 26
	s_add_i32 s9, s3, s9
	s_ashr_i32 s36, s9, 6
	s_lshl_b32 s36, s36, 3
	s_sub_i32 s37, s15, s36
	s_min_i32 s37, s37, 8
	s_abs_i32 s38, s37
	v_cvt_f32_u32_e32 v0, s38
	s_sub_i32 s40, 0, s38
	s_andn2_b32 s9, s9, 63
	s_sub_i32 s3, s3, s9
	v_rcp_iflag_f32_e32 v0, v0
	s_abs_i32 s9, s3
	s_xor_b32 s39, s3, s37
	s_ashr_i32 s39, s39, 31
	v_mul_f32_e32 v0, 0x4f7ffffe, v0
	v_cvt_u32_f32_e32 v0, v0
	s_nop 0
	v_readfirstlane_b32 s41, v0
	s_mul_i32 s40, s40, s41
	s_mul_hi_u32 s40, s41, s40
	s_add_i32 s41, s41, s40
	s_mul_hi_u32 s40, s9, s41
	s_mul_i32 s41, s40, s38
	s_sub_i32 s9, s9, s41
	s_add_i32 s42, s40, 1
	s_sub_i32 s41, s9, s38
	s_cmp_ge_u32 s9, s38
	s_cselect_b32 s40, s42, s40
	s_cselect_b32 s9, s41, s9
	s_add_i32 s41, s40, 1
	s_cmp_ge_u32 s9, s38
	s_cselect_b32 s9, s41, s40
	s_xor_b32 s9, s9, s39
	s_sub_i32 s58, s9, s39
	s_mul_i32 s9, s58, s37
	s_sub_i32 s3, s3, s9
	s_add_i32 s60, s3, s36
.LBB0_204:
	s_ashr_i32 s61, s60, 31
	s_lshl_b64 s[36:37], s[60:61], 20
	s_add_u32 s62, s45, s36
	s_addc_u32 s63, s44, s37
	s_and_b64 s[36:37], s[6:7], exec
	s_cselect_b32 s9, s63, s69
	s_cselect_b32 s61, s62, s68
	s_ashr_i32 s59, s58, 31
	s_lshl_b64 s[36:37], s[58:59], 20
	s_add_u32 s64, s54, s36
	s_addc_u32 s65, s55, s37
	s_and_b64 s[36:37], s[6:7], exec
	s_cselect_b32 s59, s65, s71
	s_cselect_b32 s87, s64, s70
	s_add_u32 s68, s68, 0x80080
	s_addc_u32 s69, s69, 0
	s_add_u32 s3, s70, 0x100
	s_addc_u32 s88, s71, 0
	s_mov_b32 s89, -2
	s_nop 0
	s_add_u32 s36, s68, 0xfff80080
	s_addc_u32 s37, s69, -1
	s_add_i32 s38, 0, 0x10000
	s_cmp_eq_u32 s89, 28
	s_cselect_b32 s73, s9, s37
	s_cselect_b32 s72, s61, s36
	s_cselect_b32 s71, s59, s88
	s_cselect_b32 s70, s87, s3
	s_add_i32 s39, 0, 0x14000
	s_add_i32 m0, s67, 0xc000
	global_load_lds_dwordx4 v196, s[68:69]
	s_add_i32 m0, s67, 0xe000
	s_nop 0
	global_load_lds_dwordx4 v198, s[68:69]
	s_waitcnt vmcnt(24)
	s_waitcnt lgkmcnt(0)
	s_barrier
	s_setprio 1
	s_waitcnt lgkmcnt(0)
	v_mfma_f32_16x16x32_bf16 v[148:151], v[80:83], v[160:163], 0
	v_mfma_f32_16x16x32_bf16 v[148:151], v[88:91], v[164:167], v[148:151]
	v_mfma_f32_16x16x32_bf16 v[144:147], v[104:107], v[160:163], 0
	v_mfma_f32_16x16x32_bf16 v[144:147], v[108:111], v[164:167], v[144:147]
	v_mfma_f32_16x16x32_bf16 v[124:127], v[80:83], v[168:171], 0
	v_mfma_f32_16x16x32_bf16 v[124:127], v[88:91], v[172:175], v[124:127]
	v_mfma_f32_16x16x32_bf16 v[120:123], v[104:107], v[168:171], 0
	v_mfma_f32_16x16x32_bf16 v[120:123], v[108:111], v[172:175], v[120:123]
	v_mfma_f32_16x16x32_bf16 v[100:103], v[80:83], v[176:179], 0
	v_mfma_f32_16x16x32_bf16 v[100:103], v[88:91], v[180:183], v[100:103]
	v_mfma_f32_16x16x32_bf16 v[96:99], v[104:107], v[176:179], 0
	v_mfma_f32_16x16x32_bf16 v[96:99], v[108:111], v[180:183], v[96:99]
	v_mfma_f32_16x16x32_bf16 v[76:79], v[80:83], v[184:187], 0
	v_mfma_f32_16x16x32_bf16 v[76:79], v[88:91], v[200:203], v[76:79]
	v_mfma_f32_16x16x32_bf16 v[72:75], v[104:107], v[184:187], 0
	v_mfma_f32_16x16x32_bf16 v[72:75], v[108:111], v[200:203], v[72:75]
	s_setprio 0
	s_setprio 1
	v_mfma_f32_16x16x32_bf16 v[140:143], v[128:131], v[160:163], 0
	v_mfma_f32_16x16x32_bf16 v[140:143], v[132:135], v[164:167], v[140:143]
	v_mfma_f32_16x16x32_bf16 v[136:139], v[152:155], v[160:163], 0
	v_mfma_f32_16x16x32_bf16 v[136:139], v[156:159], v[164:167], v[136:139]
	v_mfma_f32_16x16x32_bf16 v[116:119], v[128:131], v[168:171], 0
	v_mfma_f32_16x16x32_bf16 v[116:119], v[132:135], v[172:175], v[116:119]
	v_mfma_f32_16x16x32_bf16 v[112:115], v[152:155], v[168:171], 0
	v_mfma_f32_16x16x32_bf16 v[112:115], v[156:159], v[172:175], v[112:115]
	v_mfma_f32_16x16x32_bf16 v[92:95], v[128:131], v[176:179], 0
	v_mfma_f32_16x16x32_bf16 v[92:95], v[132:135], v[180:183], v[92:95]
	v_mfma_f32_16x16x32_bf16 v[84:87], v[152:155], v[176:179], 0
	v_mfma_f32_16x16x32_bf16 v[84:87], v[156:159], v[180:183], v[84:87]
	v_mfma_f32_16x16x32_bf16 v[68:71], v[128:131], v[184:187], 0
	v_mfma_f32_16x16x32_bf16 v[68:71], v[132:135], v[200:203], v[68:71]
	v_mfma_f32_16x16x32_bf16 v[64:67], v[152:155], v[184:187], 0
	v_mfma_f32_16x16x32_bf16 v[64:67], v[156:159], v[200:203], v[64:67]
	s_setprio 0
	s_barrier
; #define PG8_STAGE(bufoff, gbase, voff) do { _Pragma("unroll") for (int _i = 0; _i < 2; ++_i) \
;         __builtin_amdgcn_global_load_lds((const unsigned*)((const char*)(gbase) + (voff)[_i]), (PG8_LAS unsigned*)(lds + (bufoff) + ldsw + _i * 8192), 16, 0, 0); } while (0)
; #define PG8_LDA(dst, b, h) do { _Pragma("unroll") for (int m = 0; m < 4; ++m) _Pragma("unroll") for (int k = 0; k < 2; ++k) dst[m][k] = *(const PG8_LAS bf16x8*)(lds + PG8_SA(b, h) + aoff + m * 2048 + k * 1024); } while (0)
; #define PG8_LDB(dst, b, h) do { _Pragma("unroll") for (int n = 0; n < 2; ++n) _Pragma("unroll") for (int k = 0; k < 2; ++k) dst[n][k] = *(const PG8_LAS bf16x8*)(lds + PG8_SB(b, h) + boff + n * 2048 + k * 1024); } while (0)
; #define PG8_MMA(ai, bj, At, Bt) do { __builtin_amdgcn_s_setprio(1); _Pragma("unroll") for (int m = 0; m < 4; ++m) _Pragma("unroll") for (int n = 0; n < 2; ++n) _Pragma("unroll") for (int k = 0; k < 2; ++k) \
;         acc[ai][bj][m][n] = __builtin_amdgcn_mfma_f32_16x16x32_bf16(Bt[n][k], At[m][k], acc[ai][bj][m][n], 0, 0, 0); __builtin_amdgcn_s_setprio(0); } while (0)
; #define PG8_WAIT_V(n) asm volatile("s_waitcnt vmcnt(" #n ")" ::: "memory")
; #define PG8_WAIT_L(n) asm volatile("s_waitcnt lgkmcnt(" #n ")" ::: "memory")
; #define PG8_BAR __builtin_amdgcn_s_barrier()
; #define PG8_SCHED __builtin_amdgcn_sched_barrier(0)
; template <class Epi, class Sched, bool ALIGN_EPI = false, bool SP2 = false>
; __device__ __forceinline__ void gemm_phase(PG8_LAS unsigned char* lds, const Gemm g, const Sched& S, const Epi& E) {
;     ...
;             PG8_LDA(At, 0, 1); PG8_STAGE(PG8_SB(0, 0), b2, voffB); PG8_STAGE(PG8_SB(0, 1), b2 + hstep, voffB); PG8_STAGE(PG8_SA(0, 0), a2, voffA);
;             PG8_WAIT_V(8); PG8_WAIT_L(0); PG8_BAR; PG8_MMA(1, 0, At, B0); PG8_MMA(1, 1, At, B1); PG8_BAR; PG8_SCHED;
;             PG8_LDB(B0, 1, 0); PG8_LDB(B1, 1, 1); PG8_SCHED; PG8_LDA(At, 1, 0); PG8_STAGE(PG8_SA(0, 1), a2 + hstep, voffA);
;             PG8_WAIT_V(8); PG8_WAIT_L(0); PG8_BAR; PG8_MMA(0, 0, At, B0); PG8_MMA(0, 1, At, B1); PG8_BAR; PG8_SCHED;
	s_add_i32 s36, s38, s75
	s_mov_b32 m0, s36
	ds_read_b128 v[160:163], v240 offset:16384
	ds_read_b128 v[164:167], v240 offset:17408
	ds_read_b128 v[168:171], v240 offset:18432
	ds_read_b128 v[172:175], v240 offset:19456
	ds_read_b128 v[176:179], v240 offset:20480
	ds_read_b128 v[180:183], v240 offset:21504
	ds_read_b128 v[184:187], v240 offset:22528
	ds_read_b128 v[200:203], v240 offset:23552
	global_load_lds_dwordx4 v188, s[70:71]
	s_add_i32 m0, s36, 0x2000
	s_add_u32 s36, s70, 0x80000
	s_addc_u32 s37, s71, 0
	s_add_i32 s38, s39, s75
	global_load_lds_dwordx4 v194, s[70:71]
	s_mov_b32 m0, s38
	s_nop 0
	global_load_lds_dwordx4 v188, s[36:37]
	s_add_i32 m0, s38, 0x2000
	s_nop 0
	global_load_lds_dwordx4 v194, s[36:37]
	s_mov_b32 m0, s67
	s_nop 0
	global_load_lds_dwordx4 v188, s[72:73]
	s_mov_b32 m0, s76
	s_nop 0
	global_load_lds_dwordx4 v194, s[72:73]
	s_waitcnt vmcnt(24)
	s_waitcnt lgkmcnt(0)
	s_barrier
	s_setprio 1
	s_waitcnt lgkmcnt(0)
	v_mfma_f32_16x16x32_bf16 v[60:63], v[80:83], v[160:163], 0
	v_mfma_f32_16x16x32_bf16 v[60:63], v[88:91], v[164:167], v[60:63]
	v_mfma_f32_16x16x32_bf16 v[56:59], v[104:107], v[160:163], 0
	v_mfma_f32_16x16x32_bf16 v[56:59], v[108:111], v[164:167], v[56:59]
	v_mfma_f32_16x16x32_bf16 v[44:47], v[80:83], v[168:171], 0
	v_mfma_f32_16x16x32_bf16 v[44:47], v[88:91], v[172:175], v[44:47]
	v_mfma_f32_16x16x32_bf16 v[40:43], v[104:107], v[168:171], 0
	v_mfma_f32_16x16x32_bf16 v[40:43], v[108:111], v[172:175], v[40:43]
	v_mfma_f32_16x16x32_bf16 v[28:31], v[80:83], v[176:179], 0
	v_mfma_f32_16x16x32_bf16 v[28:31], v[88:91], v[180:183], v[28:31]
	v_mfma_f32_16x16x32_bf16 v[24:27], v[104:107], v[176:179], 0
	v_mfma_f32_16x16x32_bf16 v[24:27], v[108:111], v[180:183], v[24:27]
	v_mfma_f32_16x16x32_bf16 v[12:15], v[80:83], v[184:187], 0
	v_mfma_f32_16x16x32_bf16 v[12:15], v[88:91], v[200:203], v[12:15]
	v_mfma_f32_16x16x32_bf16 v[8:11], v[104:107], v[184:187], 0
	v_mfma_f32_16x16x32_bf16 v[8:11], v[108:111], v[200:203], v[8:11]
	s_setprio 0
	s_setprio 1
	v_mfma_f32_16x16x32_bf16 v[52:55], v[128:131], v[160:163], 0
	v_mfma_f32_16x16x32_bf16 v[52:55], v[132:135], v[164:167], v[52:55]
	v_mfma_f32_16x16x32_bf16 v[48:51], v[152:155], v[160:163], 0
	v_mfma_f32_16x16x32_bf16 v[48:51], v[156:159], v[164:167], v[48:51]
	v_mfma_f32_16x16x32_bf16 v[36:39], v[128:131], v[168:171], 0
	v_mfma_f32_16x16x32_bf16 v[36:39], v[132:135], v[172:175], v[36:39]
	v_mfma_f32_16x16x32_bf16 v[32:35], v[152:155], v[168:171], 0
	v_mfma_f32_16x16x32_bf16 v[32:35], v[156:159], v[172:175], v[32:35]
	v_mfma_f32_16x16x32_bf16 v[20:23], v[128:131], v[176:179], 0
	v_mfma_f32_16x16x32_bf16 v[20:23], v[132:135], v[180:183], v[20:23]
	v_mfma_f32_16x16x32_bf16 v[16:19], v[152:155], v[176:179], 0
	v_mfma_f32_16x16x32_bf16 v[16:19], v[156:159], v[180:183], v[16:19]
	v_mfma_f32_16x16x32_bf16 v[4:7], v[128:131], v[184:187], 0
	v_mfma_f32_16x16x32_bf16 v[4:7], v[132:135], v[200:203], v[4:7]
	v_mfma_f32_16x16x32_bf16 v[0:3], v[152:155], v[184:187], 0
	v_mfma_f32_16x16x32_bf16 v[0:3], v[156:159], v[200:203], v[0:3]
	s_setprio 0
	s_barrier
	s_add_i32 s38, 0, 0x18000
	s_add_i32 s39, 0, 0x1c000
	ds_read_b128 v[80:83], v204 offset:32768
	ds_read_b128 v[88:91], v204 offset:33792
	ds_read_b128 v[104:107], v204 offset:34816
	ds_read_b128 v[108:111], v204 offset:35840
	ds_read_b128 v[128:131], v204 offset:49152
	ds_read_b128 v[132:135], v204 offset:50176
	ds_read_b128 v[152:155], v204 offset:51200
	ds_read_b128 v[156:159], v204 offset:52224
	s_add_u32 s36, s72, 0x80000
	s_addc_u32 s37, s73, 0
	s_mov_b32 m0, s77
	ds_read_b128 v[160:163], v240 offset:32768
	ds_read_b128 v[164:167], v240 offset:33792
	ds_read_b128 v[168:171], v240 offset:34816
	ds_read_b128 v[172:175], v240 offset:35840
	ds_read_b128 v[176:179], v240 offset:36864
	ds_read_b128 v[180:183], v240 offset:37888
	ds_read_b128 v[184:187], v240 offset:38912
	ds_read_b128 v[200:203], v240 offset:39936
	global_load_lds_dwordx4 v188, s[36:37]
	s_mov_b32 m0, s78
	s_nop 0
	global_load_lds_dwordx4 v194, s[36:37]
	s_waitcnt vmcnt(8)
	s_waitcnt lgkmcnt(0)
	s_barrier
; #define PG8_STAGE(bufoff, gbase, voff) do { _Pragma("unroll") for (int _i = 0; _i < 2; ++_i) \
;         __builtin_amdgcn_global_load_lds((const unsigned*)((const char*)(gbase) + (voff)[_i]), (PG8_LAS unsigned*)(lds + (bufoff) + ldsw + _i * 8192), 16, 0, 0); } while (0)
; #define PG8_LDA(dst, b, h) do { _Pragma("unroll") for (int m = 0; m < 4; ++m) _Pragma("unroll") for (int k = 0; k < 2; ++k) dst[m][k] = *(const PG8_LAS bf16x8*)(lds + PG8_SA(b, h) + aoff + m * 2048 + k * 1024); } while (0)
; #define PG8_MMA(ai, bj, At, Bt) do { __builtin_amdgcn_s_setprio(1); _Pragma("unroll") for (int m = 0; m < 4; ++m) _Pragma("unroll") for (int n = 0; n < 2; ++n) _Pragma("unroll") for (int k = 0; k < 2; ++k) \
;         acc[ai][bj][m][n] = __builtin_amdgcn_mfma_f32_16x16x32_bf16(Bt[n][k], At[m][k], acc[ai][bj][m][n], 0, 0, 0); __builtin_amdgcn_s_setprio(0); } while (0)
; #define PG8_WAIT_V(n) asm volatile("s_waitcnt vmcnt(" #n ")" ::: "memory")
; #define PG8_WAIT_L(n) asm volatile("s_waitcnt lgkmcnt(" #n ")" ::: "memory")
; #define PG8_BAR __builtin_amdgcn_s_barrier()
; #define PG8_SCHED __builtin_amdgcn_sched_barrier(0)
; template <class Epi, class Sched, bool ALIGN_EPI = false, bool SP2 = false>
; __device__ __forceinline__ void gemm_phase(PG8_LAS unsigned char* lds, const Gemm g, const Sched& S, const Epi& E) {
;     ...
;             PG8_WAIT_V(8); PG8_WAIT_L(0); PG8_BAR; PG8_MMA(0, 0, At, B0); PG8_MMA(0, 1, At, B1); PG8_BAR; PG8_SCHED;
;             PG8_LDA(At, 1, 1); PG8_STAGE(PG8_SB(1, 0), b3, voffB); PG8_STAGE(PG8_SB(1, 1), b3 + hstep, voffB); PG8_STAGE(PG8_SA(1, 0), a3, voffA);
;             PG8_WAIT_V(8); PG8_WAIT_L(0); PG8_BAR; PG8_MMA(1, 0, At, B0); PG8_MMA(1, 1, At, B1); PG8_BAR; PG8_SCHED;
	s_setprio 1
	s_waitcnt lgkmcnt(0)
	v_mfma_f32_16x16x32_bf16 v[148:151], v[80:83], v[160:163], v[148:151]
	v_mfma_f32_16x16x32_bf16 v[148:151], v[88:91], v[164:167], v[148:151]
	v_mfma_f32_16x16x32_bf16 v[144:147], v[104:107], v[160:163], v[144:147]
	v_mfma_f32_16x16x32_bf16 v[144:147], v[108:111], v[164:167], v[144:147]
	v_mfma_f32_16x16x32_bf16 v[124:127], v[80:83], v[168:171], v[124:127]
	v_mfma_f32_16x16x32_bf16 v[124:127], v[88:91], v[172:175], v[124:127]
	v_mfma_f32_16x16x32_bf16 v[120:123], v[104:107], v[168:171], v[120:123]
	v_mfma_f32_16x16x32_bf16 v[120:123], v[108:111], v[172:175], v[120:123]
	v_mfma_f32_16x16x32_bf16 v[100:103], v[80:83], v[176:179], v[100:103]
	v_mfma_f32_16x16x32_bf16 v[100:103], v[88:91], v[180:183], v[100:103]
	v_mfma_f32_16x16x32_bf16 v[96:99], v[104:107], v[176:179], v[96:99]
	v_mfma_f32_16x16x32_bf16 v[96:99], v[108:111], v[180:183], v[96:99]
	v_mfma_f32_16x16x32_bf16 v[76:79], v[80:83], v[184:187], v[76:79]
	v_mfma_f32_16x16x32_bf16 v[76:79], v[88:91], v[200:203], v[76:79]
	v_mfma_f32_16x16x32_bf16 v[72:75], v[104:107], v[184:187], v[72:75]
	v_mfma_f32_16x16x32_bf16 v[72:75], v[108:111], v[200:203], v[72:75]
	s_setprio 0
	s_setprio 1
	v_mfma_f32_16x16x32_bf16 v[140:143], v[128:131], v[160:163], v[140:143]
	v_mfma_f32_16x16x32_bf16 v[140:143], v[132:135], v[164:167], v[140:143]
	v_mfma_f32_16x16x32_bf16 v[136:139], v[152:155], v[160:163], v[136:139]
	v_mfma_f32_16x16x32_bf16 v[136:139], v[156:159], v[164:167], v[136:139]
	v_mfma_f32_16x16x32_bf16 v[116:119], v[128:131], v[168:171], v[116:119]
	v_mfma_f32_16x16x32_bf16 v[116:119], v[132:135], v[172:175], v[116:119]
	v_mfma_f32_16x16x32_bf16 v[112:115], v[152:155], v[168:171], v[112:115]
	v_mfma_f32_16x16x32_bf16 v[112:115], v[156:159], v[172:175], v[112:115]
	v_mfma_f32_16x16x32_bf16 v[92:95], v[128:131], v[176:179], v[92:95]
	v_mfma_f32_16x16x32_bf16 v[92:95], v[132:135], v[180:183], v[92:95]
	v_mfma_f32_16x16x32_bf16 v[84:87], v[152:155], v[176:179], v[84:87]
	v_mfma_f32_16x16x32_bf16 v[84:87], v[156:159], v[180:183], v[84:87]
	v_mfma_f32_16x16x32_bf16 v[68:71], v[128:131], v[184:187], v[68:71]
	v_mfma_f32_16x16x32_bf16 v[68:71], v[132:135], v[200:203], v[68:71]
	v_mfma_f32_16x16x32_bf16 v[64:67], v[152:155], v[184:187], v[64:67]
	v_mfma_f32_16x16x32_bf16 v[64:67], v[156:159], v[200:203], v[64:67]
	s_setprio 0
	s_barrier
	s_add_i32 s36, s38, s75
	s_mov_b32 m0, s36
	ds_read_b128 v[160:163], v240 offset:49152
	ds_read_b128 v[164:167], v240 offset:50176
	ds_read_b128 v[168:171], v240 offset:51200
	ds_read_b128 v[172:175], v240 offset:52224
	ds_read_b128 v[176:179], v240 offset:53248
	ds_read_b128 v[180:183], v240 offset:54272
	ds_read_b128 v[184:187], v240 offset:55296
	ds_read_b128 v[200:203], v240 offset:56320
	s_add_u32 s100, s70, 0x80
	s_addc_u32 s101, s71, 0
	global_load_lds_dwordx4 v188, s[100:101]
	s_add_i32 m0, s36, 0x2000
	s_add_u32 s36, s70, 0x80080
	s_addc_u32 s37, s71, 0
	s_add_i32 s38, s39, s75
	global_load_lds_dwordx4 v194, s[100:101]
	s_mov_b32 m0, s38
	s_nop 0
	global_load_lds_dwordx4 v188, s[36:37]
	s_add_i32 m0, s38, 0x2000
	s_nop 0
	global_load_lds_dwordx4 v194, s[36:37]
	s_mov_b32 m0, s79
	s_nop 0
	s_add_u32 s100, s72, 0x80
	s_addc_u32 s101, s73, 0
	global_load_lds_dwordx4 v188, s[100:101]
	s_mov_b32 m0, s80
	s_nop 0
	global_load_lds_dwordx4 v194, s[100:101]
	s_waitcnt vmcnt(8)
	s_waitcnt lgkmcnt(0)
	s_barrier
	s_setprio 1
	s_waitcnt lgkmcnt(0)
	v_mfma_f32_16x16x32_bf16 v[60:63], v[80:83], v[160:163], v[60:63]
	v_mfma_f32_16x16x32_bf16 v[60:63], v[88:91], v[164:167], v[60:63]
	v_mfma_f32_16x16x32_bf16 v[56:59], v[104:107], v[160:163], v[56:59]
	v_mfma_f32_16x16x32_bf16 v[56:59], v[108:111], v[164:167], v[56:59]
	v_mfma_f32_16x16x32_bf16 v[44:47], v[80:83], v[168:171], v[44:47]
	v_mfma_f32_16x16x32_bf16 v[44:47], v[88:91], v[172:175], v[44:47]
	v_mfma_f32_16x16x32_bf16 v[40:43], v[104:107], v[168:171], v[40:43]
	v_mfma_f32_16x16x32_bf16 v[40:43], v[108:111], v[172:175], v[40:43]
	v_mfma_f32_16x16x32_bf16 v[28:31], v[80:83], v[176:179], v[28:31]
	v_mfma_f32_16x16x32_bf16 v[28:31], v[88:91], v[180:183], v[28:31]
	v_mfma_f32_16x16x32_bf16 v[24:27], v[104:107], v[176:179], v[24:27]
	v_mfma_f32_16x16x32_bf16 v[24:27], v[108:111], v[180:183], v[24:27]
	v_mfma_f32_16x16x32_bf16 v[12:15], v[80:83], v[184:187], v[12:15]
	v_mfma_f32_16x16x32_bf16 v[12:15], v[88:91], v[200:203], v[12:15]
	v_mfma_f32_16x16x32_bf16 v[8:11], v[104:107], v[184:187], v[8:11]
	v_mfma_f32_16x16x32_bf16 v[8:11], v[108:111], v[200:203], v[8:11]
	s_setprio 0
	s_setprio 1
	v_mfma_f32_16x16x32_bf16 v[52:55], v[128:131], v[160:163], v[52:55]
	v_mfma_f32_16x16x32_bf16 v[52:55], v[132:135], v[164:167], v[52:55]
	v_mfma_f32_16x16x32_bf16 v[48:51], v[152:155], v[160:163], v[48:51]
	v_mfma_f32_16x16x32_bf16 v[48:51], v[156:159], v[164:167], v[48:51]
	v_mfma_f32_16x16x32_bf16 v[36:39], v[128:131], v[168:171], v[36:39]
	v_mfma_f32_16x16x32_bf16 v[36:39], v[132:135], v[172:175], v[36:39]
	v_mfma_f32_16x16x32_bf16 v[32:35], v[152:155], v[168:171], v[32:35]
	v_mfma_f32_16x16x32_bf16 v[32:35], v[156:159], v[172:175], v[32:35]
	v_mfma_f32_16x16x32_bf16 v[20:23], v[128:131], v[176:179], v[20:23]
	v_mfma_f32_16x16x32_bf16 v[20:23], v[132:135], v[180:183], v[20:23]
	v_mfma_f32_16x16x32_bf16 v[16:19], v[152:155], v[176:179], v[16:19]
	v_mfma_f32_16x16x32_bf16 v[16:19], v[156:159], v[180:183], v[16:19]
	v_mfma_f32_16x16x32_bf16 v[4:7], v[128:131], v[184:187], v[4:7]
	v_mfma_f32_16x16x32_bf16 v[4:7], v[132:135], v[200:203], v[4:7]
	v_mfma_f32_16x16x32_bf16 v[0:3], v[152:155], v[184:187], v[0:3]
	v_mfma_f32_16x16x32_bf16 v[0:3], v[156:159], v[200:203], v[0:3]
	s_setprio 0
	s_barrier
	s_add_i32 s89, s89, 2
	s_add_u32 s68, s68, 0x100
	s_addc_u32 s69, s69, 0
	s_add_u32 s3, s3, 0x100
	s_addc_u32 s88, s88, 0
	s_cmp_gt_u32 s89, 29

; #define PG8_STAGE(bufoff, gbase, voff) do { _Pragma("unroll") for (int _i = 0; _i < 2; ++_i) \
;         __builtin_amdgcn_global_load_lds((const unsigned*)((const char*)(gbase) + (voff)[_i]), (PG8_LAS unsigned*)(lds + (bufoff) + ldsw + _i * 8192), 16, 0, 0); } while (0)
; #define PG8_LDA(dst, b, h) do { _Pragma("unroll") for (int m = 0; m < 4; ++m) _Pragma("unroll") for (int k = 0; k < 2; ++k) dst[m][k] = *(const PG8_LAS bf16x8*)(lds + PG8_SA(b, h) + aoff + m * 2048 + k * 1024); } while (0)
; #define PG8_LDB(dst, b, h) do { _Pragma("unroll") for (int n = 0; n < 2; ++n) _Pragma("unroll") for (int k = 0; k < 2; ++k) dst[n][k] = *(const PG8_LAS bf16x8*)(lds + PG8_SB(b, h) + boff + n * 2048 + k * 1024); } while (0)
; #define PG8_BAR __builtin_amdgcn_s_barrier()
;     __host__ __device__ bool next(int i, Unit& u) const {
;         const long L = (long)i * G + c; if (L >= nwg) return false;
;         int wgid = (int)L; { const int q = nwg / NXCD, r = nwg % NXCD, xcd = wgid % NXCD, off = wgid / NXCD; wgid = (xcd < r ? xcd * (q + 1) : r * (q + 1) + (xcd - r) * q) + off; }
;         const int nig = WGM * nN, gid = wgid / nig, fm = gid * WGM, gsz = (nM - fm) < WGM ? (nM - fm) : WGM;
;         u.pm = fm + ((wgid % nig) % gsz); u.pn = (wgid % nig) / gsz; return true;
;     }
; template <class Epi, class Sched, bool ALIGN_EPI = false, bool SP2 = false>
; __device__ __forceinline__ void gemm_phase(PG8_LAS unsigned char* lds, const Gemm g, const Sched& S, const Epi& E) {
;     ...
;         const bool has_next = S.next(ui + 1, nxt);
;         const char* nA = has_next ? (const char*)g.A + (size_t)nxt.pm * tstep : cA; const char* nB = has_next ? (const char*)g.Bt + (size_t)nxt.pn * tstep : cB;
;         for (int t = 0; t < nt; t += 2) {
;             const bool last = (t == nt - 2);
;             const char* a1 = cA + (size_t)(t + 1) * kstep;
;             const char* a2 = last ? nA : cA + (size_t)(t + 2) * kstep; const char* b2 = last ? nB : cB + (size_t)(t + 2) * kstep;
;             const char* a3 = a2 + kstep; const char* b3 = b2 + kstep;
;             if (last && has_next) S.a_ready(nxt);
;             if constexpr (SP2) {
;             PG8_LDB(B0, 0, 0); PG8_LDB(B1, 0, 1); PG8_SCHED; PG8_LDA(At, 0, 0); PG8_STAGE(PG8_SA(1, 1), a1 + hstep, voffA);
;             PG8_WAIT_V(8); PG8_WAIT_L(0); PG8_BAR; PG8_MMA(0, 0, At, B0); PG8_MMA(0, 1, At, B1); PG8_BAR; PG8_SCHED;
.LBB0_295:
	s_waitcnt vmcnt(8)
	v_add_u32_e32 v214, 0x10000, v165
	ds_read_b128 v[64:67], v214
	ds_read_b128 v[68:71], v214 offset:1024
	ds_read_b128 v[72:75], v214 offset:2048
	ds_read_b128 v[146:149], v214 offset:3072
	ds_read_b128 v[150:153], v214 offset:16384
	ds_read_b128 v[154:157], v214 offset:17408
	ds_read_b128 v[158:161], v214 offset:18432
	ds_read_b128 v[170:173], v214 offset:19456
	ds_read_b128 v[174:177], v169
	ds_read_b128 v[178:181], v169 offset:1024
	ds_read_b128 v[182:185], v169 offset:2048
	ds_read_b128 v[194:197], v169 offset:3072
	ds_read_b128 v[198:201], v169 offset:4096
	ds_read_b128 v[202:205], v169 offset:5120
	ds_read_b128 v[206:209], v169 offset:6144
	ds_read_b128 v[210:213], v169 offset:7168
	s_add_i32 s54, s54, 1
	s_mul_i32 s3, s54, s55
	s_mul_hi_u32 s12, s54, s86
	s_add_i32 s12, s12, s3
	s_mul_i32 s3, s54, s86
	s_add_u32 s76, s3, s2
	s_addc_u32 s77, s12, s33
	v_mov_b64_e32 v[0:1], s[98:99]
	v_cmp_ge_i64_e32 vcc, s[76:77], v[0:1]
	v_cmp_lt_i64_e64 s[12:13], s[76:77], v[0:1]
	s_cbranch_vccnz .LBB0_297
	s_ashr_i32 s3, s76, 31
	s_lshr_b32 s3, s3, 29
	s_add_i32 s3, s76, s3
	s_ashr_i32 s36, s3, 3
	s_and_b32 s3, s3, -8
	s_sub_i32 s3, s76, s3
	s_lshr_b32 s37, s3, 31
	s_or_b32 s37, s44, s37
	s_mul_i32 s3, s37, s3
	s_add_i32 s3, s3, s36
	s_ashr_i32 s36, s3, 31
	s_lshr_b32 s36, s36, 24
	s_add_i32 s36, s3, s36
	s_ashr_i32 s36, s36, 8
	s_lshl_b32 s37, s36, 3
	s_sub_i32 s38, s45, s37
	s_min_i32 s38, s38, 8
	v_mul_i32_i24_e32 v0, s36, v226
	s_abs_i32 s40, s38
	v_readfirstlane_b32 s36, v0
	v_cvt_f32_u32_e32 v0, s40
	s_sub_i32 s41, 0, s40
	s_sub_i32 s3, s3, s36
	s_abs_i32 s39, s3
	v_rcp_iflag_f32_e32 v0, v0
	s_xor_b32 s36, s3, s38
	s_ashr_i32 s36, s36, 31
	v_mul_f32_e32 v0, 0x4f7ffffe, v0
	v_cvt_u32_f32_e32 v0, v0
	s_nop 0
	v_readfirstlane_b32 s42, v0
	s_mul_i32 s41, s41, s42
	s_mul_hi_u32 s41, s42, s41
	s_add_i32 s42, s42, s41
	s_mul_hi_u32 s41, s39, s42
	s_mul_i32 s42, s41, s40
	s_sub_i32 s39, s39, s42
	s_add_i32 s42, s41, 1
	s_sub_i32 s43, s39, s40
	s_cmp_ge_u32 s39, s40
	s_cselect_b32 s41, s42, s41
	s_cselect_b32 s39, s43, s39
	s_add_i32 s42, s41, 1
	s_cmp_ge_u32 s39, s40
	s_cselect_b32 s39, s42, s41
	s_xor_b32 s39, s39, s36
	s_sub_i32 s74, s39, s36
	s_mul_i32 s36, s74, s38
	s_sub_i32 s3, s3, s36
	s_add_i32 s66, s3, s37
.LBB0_297:
	s_ashr_i32 s67, s66, 31
	s_lshl_b64 s[76:77], s[66:67], 20
	s_add_u32 s78, s34, s76
	s_addc_u32 s79, s35, s77
	s_and_b64 s[76:77], s[12:13], exec
	s_cselect_b32 s65, s79, s69
	s_cselect_b32 s67, s78, s68
	s_ashr_i32 s75, s74, 31
	s_lshl_b64 s[76:77], s[74:75], 20
	s_add_u32 s76, s0, s76
	s_addc_u32 s77, s1, s77
	s_and_b64 s[94:95], s[12:13], exec
	s_cselect_b32 s73, s77, s71
	s_cselect_b32 s75, s76, s70
	s_add_u32 vcc_lo, s68, 0x80080
	s_addc_u32 vcc_hi, s69, 0
	s_add_u32 s3, s70, 0x100
	s_addc_u32 s94, s71, 0
	s_mov_b32 s95, -2
	s_add_u32 s36, vcc_lo, 0xfff80080
	s_addc_u32 s37, vcc_hi, -1
	s_add_i32 s38, 0, 0x10000
	s_cmp_eq_u32 s95, 28
	s_cselect_b32 s71, s65, s37
	s_cselect_b32 s70, s67, s36
	s_cselect_b32 s69, s73, s94
	s_cselect_b32 s68, s75, s3
	s_add_i32 s39, 0, 0x14000
	s_add_i32 m0, s88, 0xc000
	global_load_lds_dwordx4 v142, vcc
	s_add_i32 m0, s88, 0xe000
	s_nop 0
	global_load_lds_dwordx4 v144, vcc
	s_waitcnt vmcnt(24)
	s_waitcnt lgkmcnt(0)
	s_barrier
	s_setprio 1
	s_waitcnt lgkmcnt(0)
	v_mfma_f32_16x16x32_bf16 v[136:139], v[64:67], v[174:177], 0
	v_mfma_f32_16x16x32_bf16 v[136:139], v[68:71], v[178:181], v[136:139]
	v_mfma_f32_16x16x32_bf16 v[132:135], v[72:75], v[174:177], 0
	v_mfma_f32_16x16x32_bf16 v[132:135], v[146:149], v[178:181], v[132:135]
	v_mfma_f32_16x16x32_bf16 v[120:123], v[64:67], v[182:185], 0
	v_mfma_f32_16x16x32_bf16 v[120:123], v[68:71], v[194:197], v[120:123]
	v_mfma_f32_16x16x32_bf16 v[116:119], v[72:75], v[182:185], 0
	v_mfma_f32_16x16x32_bf16 v[116:119], v[146:149], v[194:197], v[116:119]
	v_mfma_f32_16x16x32_bf16 v[104:107], v[64:67], v[198:201], 0
	v_mfma_f32_16x16x32_bf16 v[104:107], v[68:71], v[202:205], v[104:107]
	v_mfma_f32_16x16x32_bf16 v[100:103], v[72:75], v[198:201], 0
	v_mfma_f32_16x16x32_bf16 v[100:103], v[146:149], v[202:205], v[100:103]
	v_mfma_f32_16x16x32_bf16 v[88:91], v[64:67], v[206:209], 0
	v_mfma_f32_16x16x32_bf16 v[88:91], v[68:71], v[210:213], v[88:91]
	v_mfma_f32_16x16x32_bf16 v[84:87], v[72:75], v[206:209], 0
	v_mfma_f32_16x16x32_bf16 v[84:87], v[146:149], v[210:213], v[84:87]
	s_setprio 0
	s_setprio 1
	v_mfma_f32_16x16x32_bf16 v[128:131], v[150:153], v[174:177], 0
	v_mfma_f32_16x16x32_bf16 v[128:131], v[154:157], v[178:181], v[128:131]
	v_mfma_f32_16x16x32_bf16 v[124:127], v[158:161], v[174:177], 0
	v_mfma_f32_16x16x32_bf16 v[124:127], v[170:173], v[178:181], v[124:127]
	v_mfma_f32_16x16x32_bf16 v[112:115], v[150:153], v[182:185], 0
	v_mfma_f32_16x16x32_bf16 v[112:115], v[154:157], v[194:197], v[112:115]
	v_mfma_f32_16x16x32_bf16 v[108:111], v[158:161], v[182:185], 0
	v_mfma_f32_16x16x32_bf16 v[108:111], v[170:173], v[194:197], v[108:111]
	v_mfma_f32_16x16x32_bf16 v[96:99], v[150:153], v[198:201], 0
	v_mfma_f32_16x16x32_bf16 v[96:99], v[154:157], v[202:205], v[96:99]
	v_mfma_f32_16x16x32_bf16 v[92:95], v[158:161], v[198:201], 0
	v_mfma_f32_16x16x32_bf16 v[92:95], v[170:173], v[202:205], v[92:95]
	v_mfma_f32_16x16x32_bf16 v[80:83], v[150:153], v[206:209], 0
	v_mfma_f32_16x16x32_bf16 v[80:83], v[154:157], v[210:213], v[80:83]
	v_mfma_f32_16x16x32_bf16 v[76:79], v[158:161], v[206:209], 0
	v_mfma_f32_16x16x32_bf16 v[76:79], v[170:173], v[210:213], v[76:79]
	s_setprio 0
	s_barrier
; #define PG8_STAGE(bufoff, gbase, voff) do { _Pragma("unroll") for (int _i = 0; _i < 2; ++_i) \
;         __builtin_amdgcn_global_load_lds((const unsigned*)((const char*)(gbase) + (voff)[_i]), (PG8_LAS unsigned*)(lds + (bufoff) + ldsw + _i * 8192), 16, 0, 0); } while (0)
; #define PG8_LDA(dst, b, h) do { _Pragma("unroll") for (int m = 0; m < 4; ++m) _Pragma("unroll") for (int k = 0; k < 2; ++k) dst[m][k] = *(const PG8_LAS bf16x8*)(lds + PG8_SA(b, h) + aoff + m * 2048 + k * 1024); } while (0)
; #define PG8_LDB(dst, b, h) do { _Pragma("unroll") for (int n = 0; n < 2; ++n) _Pragma("unroll") for (int k = 0; k < 2; ++k) dst[n][k] = *(const PG8_LAS bf16x8*)(lds + PG8_SB(b, h) + boff + n * 2048 + k * 1024); } while (0)
; #define PG8_MMA(ai, bj, At, Bt) do { __builtin_amdgcn_s_setprio(1); _Pragma("unroll") for (int m = 0; m < 4; ++m) _Pragma("unroll") for (int n = 0; n < 2; ++n) _Pragma("unroll") for (int k = 0; k < 2; ++k) \
;         acc[ai][bj][m][n] = __builtin_amdgcn_mfma_f32_16x16x32_bf16(Bt[n][k], At[m][k], acc[ai][bj][m][n], 0, 0, 0); __builtin_amdgcn_s_setprio(0); } while (0)
; #define PG8_WAIT_V(n) asm volatile("s_waitcnt vmcnt(" #n ")" ::: "memory")
; #define PG8_WAIT_L(n) asm volatile("s_waitcnt lgkmcnt(" #n ")" ::: "memory")
; #define PG8_BAR __builtin_amdgcn_s_barrier()
; #define PG8_SCHED __builtin_amdgcn_sched_barrier(0)
; template <class Epi, class Sched, bool ALIGN_EPI = false, bool SP2 = false>
; __device__ __forceinline__ void gemm_phase(PG8_LAS unsigned char* lds, const Gemm g, const Sched& S, const Epi& E) {
;     ...
;             PG8_LDA(At, 0, 1); PG8_STAGE(PG8_SB(0, 0), b2, voffB); PG8_STAGE(PG8_SB(0, 1), b2 + hstep, voffB); PG8_STAGE(PG8_SA(0, 0), a2, voffA);
;             PG8_WAIT_V(8); PG8_WAIT_L(0); PG8_BAR; PG8_MMA(1, 0, At, B0); PG8_MMA(1, 1, At, B1); PG8_BAR; PG8_SCHED;
;             PG8_LDB(B0, 1, 0); PG8_LDB(B1, 1, 1); PG8_SCHED; PG8_LDA(At, 1, 0); PG8_STAGE(PG8_SA(0, 1), a2 + hstep, voffA);
;             PG8_WAIT_V(8); PG8_WAIT_L(0); PG8_BAR; PG8_MMA(0, 0, At, B0); PG8_MMA(0, 1, At, B1); PG8_BAR; PG8_SCHED;
	s_add_i32 s36, s38, s87
	s_mov_b32 m0, s36
	ds_read_b128 v[174:177], v169 offset:16384
	ds_read_b128 v[178:181], v169 offset:17408
	ds_read_b128 v[182:185], v169 offset:18432
	ds_read_b128 v[194:197], v169 offset:19456
	ds_read_b128 v[198:201], v169 offset:20480
	ds_read_b128 v[202:205], v169 offset:21504
	ds_read_b128 v[206:209], v169 offset:22528
	ds_read_b128 v[210:213], v169 offset:23552
	global_load_lds_dwordx4 v188, s[68:69]
	s_add_i32 m0, s36, 0x2000
	s_add_u32 s36, s68, 0x80000
	s_addc_u32 s37, s69, 0
	s_add_i32 s38, s39, s87
	global_load_lds_dwordx4 v140, s[68:69]
	s_mov_b32 m0, s38
	s_nop 0
	global_load_lds_dwordx4 v188, s[36:37]
	s_add_i32 m0, s38, 0x2000
	s_nop 0
	global_load_lds_dwordx4 v140, s[36:37]
	s_mov_b32 m0, s88
	s_nop 0
	global_load_lds_dwordx4 v188, s[70:71]
	s_mov_b32 m0, s89
	s_nop 0
	global_load_lds_dwordx4 v140, s[70:71]
	s_waitcnt vmcnt(24)
	s_waitcnt lgkmcnt(0)
	s_barrier
	s_setprio 1
	s_waitcnt lgkmcnt(0)
	v_mfma_f32_16x16x32_bf16 v[56:59], v[64:67], v[174:177], 0
	v_mfma_f32_16x16x32_bf16 v[56:59], v[68:71], v[178:181], v[56:59]
	v_mfma_f32_16x16x32_bf16 v[60:63], v[72:75], v[174:177], 0
	v_mfma_f32_16x16x32_bf16 v[60:63], v[146:149], v[178:181], v[60:63]
	v_mfma_f32_16x16x32_bf16 v[40:43], v[64:67], v[182:185], 0
	v_mfma_f32_16x16x32_bf16 v[40:43], v[68:71], v[194:197], v[40:43]
	v_mfma_f32_16x16x32_bf16 v[44:47], v[72:75], v[182:185], 0
	v_mfma_f32_16x16x32_bf16 v[44:47], v[146:149], v[194:197], v[44:47]
	v_mfma_f32_16x16x32_bf16 v[24:27], v[64:67], v[198:201], 0
	v_mfma_f32_16x16x32_bf16 v[24:27], v[68:71], v[202:205], v[24:27]
	v_mfma_f32_16x16x32_bf16 v[28:31], v[72:75], v[198:201], 0
	v_mfma_f32_16x16x32_bf16 v[28:31], v[146:149], v[202:205], v[28:31]
	v_mfma_f32_16x16x32_bf16 v[8:11], v[64:67], v[206:209], 0
	v_mfma_f32_16x16x32_bf16 v[8:11], v[68:71], v[210:213], v[8:11]
	v_mfma_f32_16x16x32_bf16 v[12:15], v[72:75], v[206:209], 0
	v_mfma_f32_16x16x32_bf16 v[12:15], v[146:149], v[210:213], v[12:15]
	s_setprio 0
	s_setprio 1
	v_mfma_f32_16x16x32_bf16 v[52:55], v[150:153], v[174:177], 0
	v_mfma_f32_16x16x32_bf16 v[52:55], v[154:157], v[178:181], v[52:55]
	v_mfma_f32_16x16x32_bf16 v[48:51], v[158:161], v[174:177], 0
	v_mfma_f32_16x16x32_bf16 v[48:51], v[170:173], v[178:181], v[48:51]
	v_mfma_f32_16x16x32_bf16 v[36:39], v[150:153], v[182:185], 0
	v_mfma_f32_16x16x32_bf16 v[36:39], v[154:157], v[194:197], v[36:39]
	v_mfma_f32_16x16x32_bf16 v[32:35], v[158:161], v[182:185], 0
	v_mfma_f32_16x16x32_bf16 v[32:35], v[170:173], v[194:197], v[32:35]
	v_mfma_f32_16x16x32_bf16 v[20:23], v[150:153], v[198:201], 0
	v_mfma_f32_16x16x32_bf16 v[20:23], v[154:157], v[202:205], v[20:23]
	v_mfma_f32_16x16x32_bf16 v[16:19], v[158:161], v[198:201], 0
	v_mfma_f32_16x16x32_bf16 v[16:19], v[170:173], v[202:205], v[16:19]
	v_mfma_f32_16x16x32_bf16 v[4:7], v[150:153], v[206:209], 0
	v_mfma_f32_16x16x32_bf16 v[4:7], v[154:157], v[210:213], v[4:7]
	v_mfma_f32_16x16x32_bf16 v[0:3], v[158:161], v[206:209], 0
	v_mfma_f32_16x16x32_bf16 v[0:3], v[170:173], v[210:213], v[0:3]
	s_setprio 0
	s_barrier
	s_add_i32 s38, 0, 0x18000
	s_add_i32 s39, 0, 0x1c000
	ds_read_b128 v[64:67], v214 offset:32768
	ds_read_b128 v[68:71], v214 offset:33792
	ds_read_b128 v[72:75], v214 offset:34816
	ds_read_b128 v[146:149], v214 offset:35840
	ds_read_b128 v[150:153], v214 offset:49152
	ds_read_b128 v[154:157], v214 offset:50176
	ds_read_b128 v[158:161], v214 offset:51200
	ds_read_b128 v[170:173], v214 offset:52224
	s_add_u32 s36, s70, 0x80000
	s_addc_u32 s37, s71, 0
	s_mov_b32 m0, s14
	ds_read_b128 v[174:177], v169 offset:32768
	ds_read_b128 v[178:181], v169 offset:33792
	ds_read_b128 v[182:185], v169 offset:34816
	ds_read_b128 v[194:197], v169 offset:35840
	ds_read_b128 v[198:201], v169 offset:36864
	ds_read_b128 v[202:205], v169 offset:37888
	ds_read_b128 v[206:209], v169 offset:38912
	ds_read_b128 v[210:213], v169 offset:39936
	global_load_lds_dwordx4 v188, s[36:37]
	s_mov_b32 m0, s15
	s_nop 0
	global_load_lds_dwordx4 v140, s[36:37]
	s_waitcnt vmcnt(8)
	s_waitcnt lgkmcnt(0)
	s_barrier
; #define PG8_STAGE(bufoff, gbase, voff) do { _Pragma("unroll") for (int _i = 0; _i < 2; ++_i) \
;         __builtin_amdgcn_global_load_lds((const unsigned*)((const char*)(gbase) + (voff)[_i]), (PG8_LAS unsigned*)(lds + (bufoff) + ldsw + _i * 8192), 16, 0, 0); } while (0)
; #define PG8_LDA(dst, b, h) do { _Pragma("unroll") for (int m = 0; m < 4; ++m) _Pragma("unroll") for (int k = 0; k < 2; ++k) dst[m][k] = *(const PG8_LAS bf16x8*)(lds + PG8_SA(b, h) + aoff + m * 2048 + k * 1024); } while (0)
; #define PG8_MMA(ai, bj, At, Bt) do { __builtin_amdgcn_s_setprio(1); _Pragma("unroll") for (int m = 0; m < 4; ++m) _Pragma("unroll") for (int n = 0; n < 2; ++n) _Pragma("unroll") for (int k = 0; k < 2; ++k) \
;         acc[ai][bj][m][n] = __builtin_amdgcn_mfma_f32_16x16x32_bf16(Bt[n][k], At[m][k], acc[ai][bj][m][n], 0, 0, 0); __builtin_amdgcn_s_setprio(0); } while (0)
; #define PG8_WAIT_V(n) asm volatile("s_waitcnt vmcnt(" #n ")" ::: "memory")
; #define PG8_WAIT_L(n) asm volatile("s_waitcnt lgkmcnt(" #n ")" ::: "memory")
; #define PG8_BAR __builtin_amdgcn_s_barrier()
; #define PG8_SCHED __builtin_amdgcn_sched_barrier(0)
; template <class Epi, class Sched, bool ALIGN_EPI = false, bool SP2 = false>
; __device__ __forceinline__ void gemm_phase(PG8_LAS unsigned char* lds, const Gemm g, const Sched& S, const Epi& E) {
;     ...
;             PG8_WAIT_V(8); PG8_WAIT_L(0); PG8_BAR; PG8_MMA(0, 0, At, B0); PG8_MMA(0, 1, At, B1); PG8_BAR; PG8_SCHED;
;             PG8_LDA(At, 1, 1); PG8_STAGE(PG8_SB(1, 0), b3, voffB); PG8_STAGE(PG8_SB(1, 1), b3 + hstep, voffB); PG8_STAGE(PG8_SA(1, 0), a3, voffA);
;             PG8_WAIT_V(8); PG8_WAIT_L(0); PG8_BAR; PG8_MMA(1, 0, At, B0); PG8_MMA(1, 1, At, B1); PG8_BAR; PG8_SCHED;
	s_setprio 1
	s_waitcnt lgkmcnt(0)
	v_mfma_f32_16x16x32_bf16 v[136:139], v[64:67], v[174:177], v[136:139]
	v_mfma_f32_16x16x32_bf16 v[136:139], v[68:71], v[178:181], v[136:139]
	v_mfma_f32_16x16x32_bf16 v[132:135], v[72:75], v[174:177], v[132:135]
	v_mfma_f32_16x16x32_bf16 v[132:135], v[146:149], v[178:181], v[132:135]
	v_mfma_f32_16x16x32_bf16 v[120:123], v[64:67], v[182:185], v[120:123]
	v_mfma_f32_16x16x32_bf16 v[120:123], v[68:71], v[194:197], v[120:123]
	v_mfma_f32_16x16x32_bf16 v[116:119], v[72:75], v[182:185], v[116:119]
	v_mfma_f32_16x16x32_bf16 v[116:119], v[146:149], v[194:197], v[116:119]
	v_mfma_f32_16x16x32_bf16 v[104:107], v[64:67], v[198:201], v[104:107]
	v_mfma_f32_16x16x32_bf16 v[104:107], v[68:71], v[202:205], v[104:107]
	v_mfma_f32_16x16x32_bf16 v[100:103], v[72:75], v[198:201], v[100:103]
	v_mfma_f32_16x16x32_bf16 v[100:103], v[146:149], v[202:205], v[100:103]
	v_mfma_f32_16x16x32_bf16 v[88:91], v[64:67], v[206:209], v[88:91]
	v_mfma_f32_16x16x32_bf16 v[88:91], v[68:71], v[210:213], v[88:91]
	v_mfma_f32_16x16x32_bf16 v[84:87], v[72:75], v[206:209], v[84:87]
	v_mfma_f32_16x16x32_bf16 v[84:87], v[146:149], v[210:213], v[84:87]
	s_setprio 0
	s_setprio 1
	v_mfma_f32_16x16x32_bf16 v[128:131], v[150:153], v[174:177], v[128:131]
	v_mfma_f32_16x16x32_bf16 v[128:131], v[154:157], v[178:181], v[128:131]
	v_mfma_f32_16x16x32_bf16 v[124:127], v[158:161], v[174:177], v[124:127]
	v_mfma_f32_16x16x32_bf16 v[124:127], v[170:173], v[178:181], v[124:127]
	v_mfma_f32_16x16x32_bf16 v[112:115], v[150:153], v[182:185], v[112:115]
	v_mfma_f32_16x16x32_bf16 v[112:115], v[154:157], v[194:197], v[112:115]
	v_mfma_f32_16x16x32_bf16 v[108:111], v[158:161], v[182:185], v[108:111]
	v_mfma_f32_16x16x32_bf16 v[108:111], v[170:173], v[194:197], v[108:111]
	v_mfma_f32_16x16x32_bf16 v[96:99], v[150:153], v[198:201], v[96:99]
	v_mfma_f32_16x16x32_bf16 v[96:99], v[154:157], v[202:205], v[96:99]
	v_mfma_f32_16x16x32_bf16 v[92:95], v[158:161], v[198:201], v[92:95]
	v_mfma_f32_16x16x32_bf16 v[92:95], v[170:173], v[202:205], v[92:95]
	v_mfma_f32_16x16x32_bf16 v[80:83], v[150:153], v[206:209], v[80:83]
	v_mfma_f32_16x16x32_bf16 v[80:83], v[154:157], v[210:213], v[80:83]
	v_mfma_f32_16x16x32_bf16 v[76:79], v[158:161], v[206:209], v[76:79]
	v_mfma_f32_16x16x32_bf16 v[76:79], v[170:173], v[210:213], v[76:79]
	s_setprio 0
	s_barrier
	s_add_i32 s36, s38, s87
	s_mov_b32 m0, s36
	ds_read_b128 v[174:177], v169 offset:49152
	ds_read_b128 v[178:181], v169 offset:50176
	ds_read_b128 v[182:185], v169 offset:51200
	ds_read_b128 v[194:197], v169 offset:52224
	ds_read_b128 v[198:201], v169 offset:53248
	ds_read_b128 v[202:205], v169 offset:54272
	ds_read_b128 v[206:209], v169 offset:55296
	ds_read_b128 v[210:213], v169 offset:56320
	s_add_u32 s100, s68, 0x80
	s_addc_u32 s101, s69, 0
	global_load_lds_dwordx4 v188, s[100:101]
	s_add_i32 m0, s36, 0x2000
	s_add_u32 s36, s68, 0x80080
	s_addc_u32 s37, s69, 0
	s_add_i32 s38, s39, s87
	global_load_lds_dwordx4 v140, s[100:101]
	s_mov_b32 m0, s38
	s_nop 0
	global_load_lds_dwordx4 v188, s[36:37]
	s_add_i32 m0, s38, 0x2000
	s_nop 0
	global_load_lds_dwordx4 v140, s[36:37]
	s_mov_b32 m0, s81
	s_nop 0
	s_add_u32 s100, s70, 0x80
	s_addc_u32 s101, s71, 0
	global_load_lds_dwordx4 v188, s[100:101]
	s_mov_b32 m0, s80
	s_nop 0
	global_load_lds_dwordx4 v140, s[100:101]
	s_waitcnt vmcnt(8)
	s_waitcnt lgkmcnt(0)
	s_barrier
	s_setprio 1
	s_waitcnt lgkmcnt(0)
	v_mfma_f32_16x16x32_bf16 v[56:59], v[64:67], v[174:177], v[56:59]
	v_mfma_f32_16x16x32_bf16 v[56:59], v[68:71], v[178:181], v[56:59]
	v_mfma_f32_16x16x32_bf16 v[60:63], v[72:75], v[174:177], v[60:63]
	v_mfma_f32_16x16x32_bf16 v[60:63], v[146:149], v[178:181], v[60:63]
	v_mfma_f32_16x16x32_bf16 v[40:43], v[64:67], v[182:185], v[40:43]
	v_mfma_f32_16x16x32_bf16 v[40:43], v[68:71], v[194:197], v[40:43]
	v_mfma_f32_16x16x32_bf16 v[44:47], v[72:75], v[182:185], v[44:47]
	v_mfma_f32_16x16x32_bf16 v[44:47], v[146:149], v[194:197], v[44:47]
	v_mfma_f32_16x16x32_bf16 v[24:27], v[64:67], v[198:201], v[24:27]
	v_mfma_f32_16x16x32_bf16 v[24:27], v[68:71], v[202:205], v[24:27]
	v_mfma_f32_16x16x32_bf16 v[28:31], v[72:75], v[198:201], v[28:31]
	v_mfma_f32_16x16x32_bf16 v[28:31], v[146:149], v[202:205], v[28:31]
	v_mfma_f32_16x16x32_bf16 v[8:11], v[64:67], v[206:209], v[8:11]
	v_mfma_f32_16x16x32_bf16 v[8:11], v[68:71], v[210:213], v[8:11]
	v_mfma_f32_16x16x32_bf16 v[12:15], v[72:75], v[206:209], v[12:15]
	v_mfma_f32_16x16x32_bf16 v[12:15], v[146:149], v[210:213], v[12:15]
	s_setprio 0
	s_setprio 1
	v_mfma_f32_16x16x32_bf16 v[52:55], v[150:153], v[174:177], v[52:55]
	v_mfma_f32_16x16x32_bf16 v[52:55], v[154:157], v[178:181], v[52:55]
	v_mfma_f32_16x16x32_bf16 v[48:51], v[158:161], v[174:177], v[48:51]
	v_mfma_f32_16x16x32_bf16 v[48:51], v[170:173], v[178:181], v[48:51]
	v_mfma_f32_16x16x32_bf16 v[36:39], v[150:153], v[182:185], v[36:39]
	v_mfma_f32_16x16x32_bf16 v[36:39], v[154:157], v[194:197], v[36:39]
	v_mfma_f32_16x16x32_bf16 v[32:35], v[158:161], v[182:185], v[32:35]
	v_mfma_f32_16x16x32_bf16 v[32:35], v[170:173], v[194:197], v[32:35]
	v_mfma_f32_16x16x32_bf16 v[20:23], v[150:153], v[198:201], v[20:23]
	v_mfma_f32_16x16x32_bf16 v[20:23], v[154:157], v[202:205], v[20:23]
	v_mfma_f32_16x16x32_bf16 v[16:19], v[158:161], v[198:201], v[16:19]
	v_mfma_f32_16x16x32_bf16 v[16:19], v[170:173], v[202:205], v[16:19]
	v_mfma_f32_16x16x32_bf16 v[4:7], v[150:153], v[206:209], v[4:7]
	v_mfma_f32_16x16x32_bf16 v[4:7], v[154:157], v[210:213], v[4:7]
	v_mfma_f32_16x16x32_bf16 v[0:3], v[158:161], v[206:209], v[0:3]
	v_mfma_f32_16x16x32_bf16 v[0:3], v[170:173], v[210:213], v[0:3]
	s_setprio 0
	s_barrier
	s_add_i32 s95, s95, 2
	s_add_u32 vcc_lo, vcc_lo, 0x100
	s_addc_u32 vcc_hi, vcc_hi, 0
	s_add_u32 s3, s3, 0x100
	s_addc_u32 s94, s94, 0
	s_cmp_gt_u32 s95, 29

; #define PG8_STAGE(bufoff, gbase, voff) do { _Pragma("unroll") for (int _i = 0; _i < 2; ++_i) \
;         __builtin_amdgcn_global_load_lds((const unsigned*)((const char*)(gbase) + (voff)[_i]), (PG8_LAS unsigned*)(lds + (bufoff) + ldsw + _i * 8192), 16, 0, 0); } while (0)
; #define PG8_LDA(dst, b, h) do { _Pragma("unroll") for (int m = 0; m < 4; ++m) _Pragma("unroll") for (int k = 0; k < 2; ++k) dst[m][k] = *(const PG8_LAS bf16x8*)(lds + PG8_SA(b, h) + aoff + m * 2048 + k * 1024); } while (0)
; #define PG8_LDB(dst, b, h) do { _Pragma("unroll") for (int n = 0; n < 2; ++n) _Pragma("unroll") for (int k = 0; k < 2; ++k) dst[n][k] = *(const PG8_LAS bf16x8*)(lds + PG8_SB(b, h) + boff + n * 2048 + k * 1024); } while (0)
; #define PG8_SCHED __builtin_amdgcn_sched_barrier(0)
;     __host__ __device__ bool next(int i, Unit& u) const {
;         const long L = (long)i * G + c; if (L >= nwg) return false;
;         int wgid = (int)L; { const int q = nwg / NXCD, r = nwg % NXCD, xcd = wgid % NXCD, off = wgid / NXCD; wgid = (xcd < r ? xcd * (q + 1) : r * (q + 1) + (xcd - r) * q) + off; }
; template <class Epi, class Sched, bool ALIGN_EPI = false, bool SP2 = false>
; __device__ __forceinline__ void gemm_phase(PG8_LAS unsigned char* lds, const Gemm g, const Sched& S, const Epi& E) {
;     ...
;         const bool has_next = S.next(ui + 1, nxt);
;         const char* nA = has_next ? (const char*)g.A + (size_t)nxt.pm * tstep : cA; const char* nB = has_next ? (const char*)g.Bt + (size_t)nxt.pn * tstep : cB;
;         for (int t = 0; t < nt; t += 2) {
;             const bool last = (t == nt - 2);
;             const char* a1 = cA + (size_t)(t + 1) * kstep;
;             const char* a2 = last ? nA : cA + (size_t)(t + 2) * kstep; const char* b2 = last ? nB : cB + (size_t)(t + 2) * kstep;
;             const char* a3 = a2 + kstep; const char* b3 = b2 + kstep;
;             if (last && has_next) S.a_ready(nxt);
;             if constexpr (SP2) {
;             PG8_LDB(B0, 0, 0); PG8_LDB(B1, 0, 1); PG8_SCHED; PG8_LDA(At, 0, 0); PG8_STAGE(PG8_SA(1, 1), a1 + hstep, voffA);
.LBB0_337:
	s_waitcnt vmcnt(16)
	v_add_u32_e32 v218, 0x10000, v167
	ds_read_b128 v[128:131], v218
	ds_read_b128 v[132:135], v218 offset:1024
	ds_read_b128 v[136:139], v218 offset:2048
	ds_read_b128 v[140:143], v218 offset:3072
	ds_read_b128 v[144:147], v218 offset:16384
	ds_read_b128 v[148:151], v218 offset:17408
	ds_read_b128 v[152:155], v218 offset:18432
	ds_read_b128 v[156:159], v218 offset:19456
	ds_read_b128 v[174:177], v204
	ds_read_b128 v[178:181], v204 offset:1024
	ds_read_b128 v[182:185], v204 offset:2048
	ds_read_b128 v[194:197], v204 offset:3072
	ds_read_b128 v[198:201], v204 offset:4096
	ds_read_b128 v[206:209], v204 offset:5120
	ds_read_b128 v[210:213], v204 offset:6144
	ds_read_b128 v[214:217], v204 offset:7168
	s_add_i32 s79, s79, 1
	s_mul_i32 s3, s79, s78
	s_mul_hi_u32 s4, s79, s74
	s_add_i32 s4, s4, s3
	s_mul_i32 s3, s79, s74
	s_add_u32 s44, s3, s2
	s_addc_u32 s45, s4, s33
	v_cmp_gt_i64_e32 vcc, s[44:45], v[192:193]
	v_cmp_lt_i64_e64 s[4:5], s[44:45], v[190:191]
	s_cbranch_vccnz .LBB0_343
	s_ashr_i32 s3, s44, 31
	s_lshr_b32 s3, s3, 29
	s_add_i32 s3, s44, s3
	s_and_b32 s7, s3, -8
	s_sub_i32 s7, s44, s7
	s_cmp_gt_i32 s7, 3
	s_mov_b64 s[44:45], -1
	s_cbranch_scc0 .LBB0_340
	s_mul_i32 s14, s7, 0xf2
	s_add_i32 s14, s14, 4
	s_mov_b64 s[44:45], 0

; #define PG8_STAGE(bufoff, gbase, voff) do { _Pragma("unroll") for (int _i = 0; _i < 2; ++_i) \
;         __builtin_amdgcn_global_load_lds((const unsigned*)((const char*)(gbase) + (voff)[_i]), (PG8_LAS unsigned*)(lds + (bufoff) + ldsw + _i * 8192), 16, 0, 0); } while (0)
; #define PG8_LDA(dst, b, h) do { _Pragma("unroll") for (int m = 0; m < 4; ++m) _Pragma("unroll") for (int k = 0; k < 2; ++k) dst[m][k] = *(const PG8_LAS bf16x8*)(lds + PG8_SA(b, h) + aoff + m * 2048 + k * 1024); } while (0)
; #define PG8_LDB(dst, b, h) do { _Pragma("unroll") for (int n = 0; n < 2; ++n) _Pragma("unroll") for (int k = 0; k < 2; ++k) dst[n][k] = *(const PG8_LAS bf16x8*)(lds + PG8_SB(b, h) + boff + n * 2048 + k * 1024); } while (0)
; #define PG8_WAIT_V(n) asm volatile("s_waitcnt vmcnt(" #n ")" ::: "memory")
; #define PG8_WAIT_L(n) asm volatile("s_waitcnt lgkmcnt(" #n ")" ::: "memory")
; #define PG8_BAR __builtin_amdgcn_s_barrier()
; #define PG8_SCHED __builtin_amdgcn_sched_barrier(0)
; template <class Epi, class Sched, bool ALIGN_EPI = false, bool SP2 = false>
; __device__ __forceinline__ void gemm_phase(PG8_LAS unsigned char* lds, const Gemm g, const Sched& S, const Epi& E) {
;     ...
;         const char* nA = has_next ? (const char*)g.A + (size_t)nxt.pm * tstep : cA; const char* nB = has_next ? (const char*)g.Bt + (size_t)nxt.pn * tstep : cB;
;         for (int t = 0; t < nt; t += 2) {
;             const bool last = (t == nt - 2);
;             const char* a1 = cA + (size_t)(t + 1) * kstep;
;             const char* a2 = last ? nA : cA + (size_t)(t + 2) * kstep; const char* b2 = last ? nB : cB + (size_t)(t + 2) * kstep;
;             const char* a3 = a2 + kstep; const char* b3 = b2 + kstep;
;             if (last && has_next) S.a_ready(nxt);
;             if constexpr (SP2) {
;             PG8_LDB(B0, 0, 0); PG8_LDB(B1, 0, 1); PG8_SCHED; PG8_LDA(At, 0, 0); PG8_STAGE(PG8_SA(1, 1), a1 + hstep, voffA);
;             PG8_WAIT_V(8); PG8_WAIT_L(0); PG8_BAR; PG8_MMA(0, 0, At, B0); PG8_MMA(0, 1, At, B1); PG8_BAR; PG8_SCHED;
;             PG8_LDA(At, 0, 1); PG8_STAGE(PG8_SB(0, 0), b2, voffB); PG8_STAGE(PG8_SB(0, 1), b2 + hstep, voffB); PG8_STAGE(PG8_SA(0, 0), a2, voffA);
;             PG8_WAIT_V(8); PG8_WAIT_L(0); PG8_BAR; PG8_MMA(1, 0, At, B0); PG8_MMA(1, 1, At, B1); PG8_BAR; PG8_SCHED;
.LBB0_343:
	s_ashr_i32 s57, s56, 31
	s_lshl_b64 s[14:15], s[56:57], 20
	s_add_u32 s44, s34, s14
	s_addc_u32 s45, s35, s15
	s_and_b64 s[14:15], s[4:5], exec
	s_cselect_b32 s7, s45, s9
	s_cselect_b32 s14, s44, s8
	s_ashr_i32 s61, s60, 31
	s_lshl_b64 s[54:55], s[60:61], 20
	s_add_u32 s58, s68, s54
	s_addc_u32 s59, s69, s55
	s_and_b64 s[54:55], s[4:5], exec
	s_cselect_b32 s15, s59, s11
	s_cselect_b32 s54, s58, s10
	s_add_u32 s8, s8, 0x80080
	s_addc_u32 s9, s9, 0
	s_add_u32 s55, s10, 0x100
	s_addc_u32 s3, s11, 0
	s_mov_b32 s57, -2
	s_nop 0
	s_add_u32 s10, s8, 0xfff80080
	s_addc_u32 s11, s9, -1
	s_add_i32 s36, 0, 0x10000
	s_cmp_eq_u32 s57, 28
	s_cselect_b32 s63, s7, s11
	s_cselect_b32 s62, s14, s10
	s_cselect_b32 s11, s15, s3
	s_cselect_b32 s10, s54, s55
	s_add_i32 s37, 0, 0x14000
	s_add_i32 m0, s53, 0xc000
	global_load_lds_dwordx4 v170, s[8:9]
	s_add_i32 m0, s53, 0xe000
	s_nop 0
	global_load_lds_dwordx4 v172, s[8:9]
	s_waitcnt vmcnt(24)
	s_waitcnt lgkmcnt(0)
	s_barrier
	s_setprio 1
	s_waitcnt lgkmcnt(0)
	v_mfma_f32_16x16x32_bf16 v[124:127], v[128:131], v[174:177], 0
	v_mfma_f32_16x16x32_bf16 v[124:127], v[132:135], v[178:181], v[124:127]
	v_mfma_f32_16x16x32_bf16 v[120:123], v[136:139], v[174:177], 0
	v_mfma_f32_16x16x32_bf16 v[120:123], v[140:143], v[178:181], v[120:123]
	v_mfma_f32_16x16x32_bf16 v[108:111], v[128:131], v[182:185], 0
	v_mfma_f32_16x16x32_bf16 v[108:111], v[132:135], v[194:197], v[108:111]
	v_mfma_f32_16x16x32_bf16 v[104:107], v[136:139], v[182:185], 0
	v_mfma_f32_16x16x32_bf16 v[104:107], v[140:143], v[194:197], v[104:107]
	v_mfma_f32_16x16x32_bf16 v[92:95], v[128:131], v[198:201], 0
	v_mfma_f32_16x16x32_bf16 v[92:95], v[132:135], v[206:209], v[92:95]
	v_mfma_f32_16x16x32_bf16 v[88:91], v[136:139], v[198:201], 0
	v_mfma_f32_16x16x32_bf16 v[88:91], v[140:143], v[206:209], v[88:91]
	v_mfma_f32_16x16x32_bf16 v[76:79], v[128:131], v[210:213], 0
	v_mfma_f32_16x16x32_bf16 v[76:79], v[132:135], v[214:217], v[76:79]
	v_mfma_f32_16x16x32_bf16 v[72:75], v[136:139], v[210:213], 0
	v_mfma_f32_16x16x32_bf16 v[72:75], v[140:143], v[214:217], v[72:75]
	s_setprio 0
	s_setprio 1
	v_mfma_f32_16x16x32_bf16 v[116:119], v[144:147], v[174:177], 0
	v_mfma_f32_16x16x32_bf16 v[116:119], v[148:151], v[178:181], v[116:119]
	v_mfma_f32_16x16x32_bf16 v[112:115], v[152:155], v[174:177], 0
	v_mfma_f32_16x16x32_bf16 v[112:115], v[156:159], v[178:181], v[112:115]
	v_mfma_f32_16x16x32_bf16 v[100:103], v[144:147], v[182:185], 0
	v_mfma_f32_16x16x32_bf16 v[100:103], v[148:151], v[194:197], v[100:103]
	v_mfma_f32_16x16x32_bf16 v[96:99], v[152:155], v[182:185], 0
	v_mfma_f32_16x16x32_bf16 v[96:99], v[156:159], v[194:197], v[96:99]
	v_mfma_f32_16x16x32_bf16 v[84:87], v[144:147], v[198:201], 0
	v_mfma_f32_16x16x32_bf16 v[84:87], v[148:151], v[206:209], v[84:87]
	v_mfma_f32_16x16x32_bf16 v[80:83], v[152:155], v[198:201], 0
	v_mfma_f32_16x16x32_bf16 v[80:83], v[156:159], v[206:209], v[80:83]
	v_mfma_f32_16x16x32_bf16 v[68:71], v[144:147], v[210:213], 0
	v_mfma_f32_16x16x32_bf16 v[68:71], v[148:151], v[214:217], v[68:71]
	v_mfma_f32_16x16x32_bf16 v[64:67], v[152:155], v[210:213], 0
	v_mfma_f32_16x16x32_bf16 v[64:67], v[156:159], v[214:217], v[64:67]
	s_setprio 0
	s_barrier
	s_add_i32 s36, s36, s70
	s_mov_b32 m0, s36
	ds_read_b128 v[174:177], v204 offset:16384
	ds_read_b128 v[178:181], v204 offset:17408
	ds_read_b128 v[182:185], v204 offset:18432
	ds_read_b128 v[194:197], v204 offset:19456
	ds_read_b128 v[198:201], v204 offset:20480
	ds_read_b128 v[206:209], v204 offset:21504
	ds_read_b128 v[210:213], v204 offset:22528
	ds_read_b128 v[214:217], v204 offset:23552
	global_load_lds_dwordx4 v160, s[10:11]
	s_add_i32 m0, s36, 0x2000
	s_add_u32 s64, s10, 0x80000
	s_addc_u32 s65, s11, 0
	s_add_i32 s36, s37, s70
	global_load_lds_dwordx4 v162, s[10:11]
	s_mov_b32 m0, s36
	s_nop 0
	global_load_lds_dwordx4 v160, s[64:65]
	s_add_i32 m0, s36, 0x2000
	s_nop 0
	global_load_lds_dwordx4 v162, s[64:65]
	s_mov_b32 m0, s53
	s_nop 0
	global_load_lds_dwordx4 v160, s[62:63]
	s_mov_b32 m0, s71
	s_nop 0
	global_load_lds_dwordx4 v162, s[62:63]
	s_waitcnt vmcnt(24)
	s_waitcnt lgkmcnt(0)
	s_barrier
	s_setprio 1
	s_waitcnt lgkmcnt(0)
	v_mfma_f32_16x16x32_bf16 v[60:63], v[128:131], v[174:177], 0
	v_mfma_f32_16x16x32_bf16 v[60:63], v[132:135], v[178:181], v[60:63]
	v_mfma_f32_16x16x32_bf16 v[56:59], v[136:139], v[174:177], 0
	v_mfma_f32_16x16x32_bf16 v[56:59], v[140:143], v[178:181], v[56:59]
	v_mfma_f32_16x16x32_bf16 v[44:47], v[128:131], v[182:185], 0
	v_mfma_f32_16x16x32_bf16 v[44:47], v[132:135], v[194:197], v[44:47]
	v_mfma_f32_16x16x32_bf16 v[40:43], v[136:139], v[182:185], 0
	v_mfma_f32_16x16x32_bf16 v[40:43], v[140:143], v[194:197], v[40:43]
	v_mfma_f32_16x16x32_bf16 v[28:31], v[128:131], v[198:201], 0
	v_mfma_f32_16x16x32_bf16 v[28:31], v[132:135], v[206:209], v[28:31]
	v_mfma_f32_16x16x32_bf16 v[24:27], v[136:139], v[198:201], 0
	v_mfma_f32_16x16x32_bf16 v[24:27], v[140:143], v[206:209], v[24:27]
	v_mfma_f32_16x16x32_bf16 v[12:15], v[128:131], v[210:213], 0
	v_mfma_f32_16x16x32_bf16 v[12:15], v[132:135], v[214:217], v[12:15]
	v_mfma_f32_16x16x32_bf16 v[8:11], v[136:139], v[210:213], 0
	v_mfma_f32_16x16x32_bf16 v[8:11], v[140:143], v[214:217], v[8:11]
	s_setprio 0
	s_setprio 1
	v_mfma_f32_16x16x32_bf16 v[52:55], v[144:147], v[174:177], 0
	v_mfma_f32_16x16x32_bf16 v[52:55], v[148:151], v[178:181], v[52:55]
	v_mfma_f32_16x16x32_bf16 v[48:51], v[152:155], v[174:177], 0
	v_mfma_f32_16x16x32_bf16 v[48:51], v[156:159], v[178:181], v[48:51]
	v_mfma_f32_16x16x32_bf16 v[36:39], v[144:147], v[182:185], 0
	v_mfma_f32_16x16x32_bf16 v[36:39], v[148:151], v[194:197], v[36:39]
	v_mfma_f32_16x16x32_bf16 v[32:35], v[152:155], v[182:185], 0
	v_mfma_f32_16x16x32_bf16 v[32:35], v[156:159], v[194:197], v[32:35]
	v_mfma_f32_16x16x32_bf16 v[20:23], v[144:147], v[198:201], 0
	v_mfma_f32_16x16x32_bf16 v[20:23], v[148:151], v[206:209], v[20:23]
	v_mfma_f32_16x16x32_bf16 v[16:19], v[152:155], v[198:201], 0
	v_mfma_f32_16x16x32_bf16 v[16:19], v[156:159], v[206:209], v[16:19]
	v_mfma_f32_16x16x32_bf16 v[4:7], v[144:147], v[210:213], 0
	v_mfma_f32_16x16x32_bf16 v[4:7], v[148:151], v[214:217], v[4:7]
	v_mfma_f32_16x16x32_bf16 v[0:3], v[152:155], v[210:213], 0
	v_mfma_f32_16x16x32_bf16 v[0:3], v[156:159], v[214:217], v[0:3]
	s_setprio 0
	s_barrier
; #define PG8_STAGE(bufoff, gbase, voff) do { _Pragma("unroll") for (int _i = 0; _i < 2; ++_i) \
;         __builtin_amdgcn_global_load_lds((const unsigned*)((const char*)(gbase) + (voff)[_i]), (PG8_LAS unsigned*)(lds + (bufoff) + ldsw + _i * 8192), 16, 0, 0); } while (0)
; #define PG8_LDA(dst, b, h) do { _Pragma("unroll") for (int m = 0; m < 4; ++m) _Pragma("unroll") for (int k = 0; k < 2; ++k) dst[m][k] = *(const PG8_LAS bf16x8*)(lds + PG8_SA(b, h) + aoff + m * 2048 + k * 1024); } while (0)
; #define PG8_LDB(dst, b, h) do { _Pragma("unroll") for (int n = 0; n < 2; ++n) _Pragma("unroll") for (int k = 0; k < 2; ++k) dst[n][k] = *(const PG8_LAS bf16x8*)(lds + PG8_SB(b, h) + boff + n * 2048 + k * 1024); } while (0)
; #define PG8_MMA(ai, bj, At, Bt) do { __builtin_amdgcn_s_setprio(1); _Pragma("unroll") for (int m = 0; m < 4; ++m) _Pragma("unroll") for (int n = 0; n < 2; ++n) _Pragma("unroll") for (int k = 0; k < 2; ++k) \
;         acc[ai][bj][m][n] = __builtin_amdgcn_mfma_f32_16x16x32_bf16(Bt[n][k], At[m][k], acc[ai][bj][m][n], 0, 0, 0); __builtin_amdgcn_s_setprio(0); } while (0)
; #define PG8_WAIT_V(n) asm volatile("s_waitcnt vmcnt(" #n ")" ::: "memory")
; #define PG8_WAIT_L(n) asm volatile("s_waitcnt lgkmcnt(" #n ")" ::: "memory")
; #define PG8_BAR __builtin_amdgcn_s_barrier()
; #define PG8_SCHED __builtin_amdgcn_sched_barrier(0)
; template <class Epi, class Sched, bool ALIGN_EPI = false, bool SP2 = false>
; __device__ __forceinline__ void gemm_phase(PG8_LAS unsigned char* lds, const Gemm g, const Sched& S, const Epi& E) {
;     ...
;             PG8_LDB(B0, 1, 0); PG8_LDB(B1, 1, 1); PG8_SCHED; PG8_LDA(At, 1, 0); PG8_STAGE(PG8_SA(0, 1), a2 + hstep, voffA);
;             PG8_WAIT_V(8); PG8_WAIT_L(0); PG8_BAR; PG8_MMA(0, 0, At, B0); PG8_MMA(0, 1, At, B1); PG8_BAR; PG8_SCHED;
;             PG8_LDA(At, 1, 1); PG8_STAGE(PG8_SB(1, 0), b3, voffB); PG8_STAGE(PG8_SB(1, 1), b3 + hstep, voffB); PG8_STAGE(PG8_SA(1, 0), a3, voffA);
;             PG8_WAIT_V(8); PG8_WAIT_L(0); PG8_BAR; PG8_MMA(1, 0, At, B0); PG8_MMA(1, 1, At, B1); PG8_BAR; PG8_SCHED;
	s_add_i32 s36, 0, 0x18000
	s_add_i32 s37, 0, 0x1c000
	ds_read_b128 v[128:131], v218 offset:32768
	ds_read_b128 v[132:135], v218 offset:33792
	ds_read_b128 v[136:139], v218 offset:34816
	ds_read_b128 v[140:143], v218 offset:35840
	ds_read_b128 v[144:147], v218 offset:49152
	ds_read_b128 v[148:151], v218 offset:50176
	ds_read_b128 v[152:155], v218 offset:51200
	ds_read_b128 v[156:159], v218 offset:52224
	s_add_u32 s62, s62, 0x80000
	s_addc_u32 s63, s63, 0
	s_mov_b32 m0, s72
	ds_read_b128 v[174:177], v204 offset:32768
	ds_read_b128 v[178:181], v204 offset:33792
	ds_read_b128 v[182:185], v204 offset:34816
	ds_read_b128 v[194:197], v204 offset:35840
	ds_read_b128 v[198:201], v204 offset:36864
	ds_read_b128 v[206:209], v204 offset:37888
	ds_read_b128 v[210:213], v204 offset:38912
	ds_read_b128 v[214:217], v204 offset:39936
	global_load_lds_dwordx4 v160, s[62:63]
	s_mov_b32 m0, s73
	s_nop 0
	global_load_lds_dwordx4 v162, s[62:63]
	s_waitcnt vmcnt(8)
	s_waitcnt lgkmcnt(0)
	s_barrier
	s_setprio 1
	s_waitcnt lgkmcnt(0)
	v_mfma_f32_16x16x32_bf16 v[124:127], v[128:131], v[174:177], v[124:127]
	v_mfma_f32_16x16x32_bf16 v[124:127], v[132:135], v[178:181], v[124:127]
	v_mfma_f32_16x16x32_bf16 v[120:123], v[136:139], v[174:177], v[120:123]
	v_mfma_f32_16x16x32_bf16 v[120:123], v[140:143], v[178:181], v[120:123]
	v_mfma_f32_16x16x32_bf16 v[108:111], v[128:131], v[182:185], v[108:111]
	v_mfma_f32_16x16x32_bf16 v[108:111], v[132:135], v[194:197], v[108:111]
	v_mfma_f32_16x16x32_bf16 v[104:107], v[136:139], v[182:185], v[104:107]
	v_mfma_f32_16x16x32_bf16 v[104:107], v[140:143], v[194:197], v[104:107]
	v_mfma_f32_16x16x32_bf16 v[92:95], v[128:131], v[198:201], v[92:95]
	v_mfma_f32_16x16x32_bf16 v[92:95], v[132:135], v[206:209], v[92:95]
	v_mfma_f32_16x16x32_bf16 v[88:91], v[136:139], v[198:201], v[88:91]
	v_mfma_f32_16x16x32_bf16 v[88:91], v[140:143], v[206:209], v[88:91]
	v_mfma_f32_16x16x32_bf16 v[76:79], v[128:131], v[210:213], v[76:79]
	v_mfma_f32_16x16x32_bf16 v[76:79], v[132:135], v[214:217], v[76:79]
	v_mfma_f32_16x16x32_bf16 v[72:75], v[136:139], v[210:213], v[72:75]
	v_mfma_f32_16x16x32_bf16 v[72:75], v[140:143], v[214:217], v[72:75]
	s_setprio 0
	s_setprio 1
	v_mfma_f32_16x16x32_bf16 v[116:119], v[144:147], v[174:177], v[116:119]
	v_mfma_f32_16x16x32_bf16 v[116:119], v[148:151], v[178:181], v[116:119]
	v_mfma_f32_16x16x32_bf16 v[112:115], v[152:155], v[174:177], v[112:115]
	v_mfma_f32_16x16x32_bf16 v[112:115], v[156:159], v[178:181], v[112:115]
	v_mfma_f32_16x16x32_bf16 v[100:103], v[144:147], v[182:185], v[100:103]
	v_mfma_f32_16x16x32_bf16 v[100:103], v[148:151], v[194:197], v[100:103]
	v_mfma_f32_16x16x32_bf16 v[96:99], v[152:155], v[182:185], v[96:99]
	v_mfma_f32_16x16x32_bf16 v[96:99], v[156:159], v[194:197], v[96:99]
	v_mfma_f32_16x16x32_bf16 v[84:87], v[144:147], v[198:201], v[84:87]
	v_mfma_f32_16x16x32_bf16 v[84:87], v[148:151], v[206:209], v[84:87]
	v_mfma_f32_16x16x32_bf16 v[80:83], v[152:155], v[198:201], v[80:83]
	v_mfma_f32_16x16x32_bf16 v[80:83], v[156:159], v[206:209], v[80:83]
	v_mfma_f32_16x16x32_bf16 v[68:71], v[144:147], v[210:213], v[68:71]
	v_mfma_f32_16x16x32_bf16 v[68:71], v[148:151], v[214:217], v[68:71]
	v_mfma_f32_16x16x32_bf16 v[64:67], v[152:155], v[210:213], v[64:67]
	v_mfma_f32_16x16x32_bf16 v[64:67], v[156:159], v[214:217], v[64:67]
	s_setprio 0
	s_barrier
	s_add_i32 s36, s36, s70
	s_mov_b32 m0, s36
	ds_read_b128 v[174:177], v204 offset:49152
	ds_read_b128 v[178:181], v204 offset:50176
	ds_read_b128 v[182:185], v204 offset:51200
	ds_read_b128 v[194:197], v204 offset:52224
	ds_read_b128 v[198:201], v204 offset:53248
	ds_read_b128 v[206:209], v204 offset:54272
	ds_read_b128 v[210:213], v204 offset:55296
	ds_read_b128 v[214:217], v204 offset:56320
	s_add_u32 s100, s10, 0x80
	s_addc_u32 s101, s11, 0
	global_load_lds_dwordx4 v160, s[100:101]
	s_add_i32 m0, s36, 0x2000
	s_add_u32 s10, s10, 0x80080
	s_addc_u32 s11, s11, 0
	s_add_i32 s36, s37, s70
	s_add_u32 s100, s10, 0xfff80000
	s_addc_u32 s101, s11, -1
	global_load_lds_dwordx4 v162, s[100:101]
	s_mov_b32 m0, s36
	s_nop 0
	global_load_lds_dwordx4 v160, s[10:11]
	s_add_i32 m0, s36, 0x2000
	s_nop 0
	global_load_lds_dwordx4 v162, s[10:11]
	s_mov_b32 m0, s76
	s_nop 0
	s_add_u32 s100, s62, 0xfff80080
	s_addc_u32 s101, s63, -1
	global_load_lds_dwordx4 v160, s[100:101]
	s_mov_b32 m0, s77
	s_nop 0
	global_load_lds_dwordx4 v162, s[100:101]
	s_waitcnt vmcnt(8)
	s_waitcnt lgkmcnt(0)
	s_barrier
	s_setprio 1
	s_waitcnt lgkmcnt(0)
	v_mfma_f32_16x16x32_bf16 v[60:63], v[128:131], v[174:177], v[60:63]
	v_mfma_f32_16x16x32_bf16 v[60:63], v[132:135], v[178:181], v[60:63]
	v_mfma_f32_16x16x32_bf16 v[56:59], v[136:139], v[174:177], v[56:59]
	v_mfma_f32_16x16x32_bf16 v[56:59], v[140:143], v[178:181], v[56:59]
	v_mfma_f32_16x16x32_bf16 v[44:47], v[128:131], v[182:185], v[44:47]
	v_mfma_f32_16x16x32_bf16 v[44:47], v[132:135], v[194:197], v[44:47]
	v_mfma_f32_16x16x32_bf16 v[40:43], v[136:139], v[182:185], v[40:43]
	v_mfma_f32_16x16x32_bf16 v[40:43], v[140:143], v[194:197], v[40:43]
	v_mfma_f32_16x16x32_bf16 v[28:31], v[128:131], v[198:201], v[28:31]
	v_mfma_f32_16x16x32_bf16 v[28:31], v[132:135], v[206:209], v[28:31]
	v_mfma_f32_16x16x32_bf16 v[24:27], v[136:139], v[198:201], v[24:27]
	v_mfma_f32_16x16x32_bf16 v[24:27], v[140:143], v[206:209], v[24:27]
	v_mfma_f32_16x16x32_bf16 v[12:15], v[128:131], v[210:213], v[12:15]
	v_mfma_f32_16x16x32_bf16 v[12:15], v[132:135], v[214:217], v[12:15]
	v_mfma_f32_16x16x32_bf16 v[8:11], v[136:139], v[210:213], v[8:11]
	v_mfma_f32_16x16x32_bf16 v[8:11], v[140:143], v[214:217], v[8:11]
	s_setprio 0
	s_setprio 1
	v_mfma_f32_16x16x32_bf16 v[52:55], v[144:147], v[174:177], v[52:55]
	v_mfma_f32_16x16x32_bf16 v[52:55], v[148:151], v[178:181], v[52:55]
	v_mfma_f32_16x16x32_bf16 v[48:51], v[152:155], v[174:177], v[48:51]
	v_mfma_f32_16x16x32_bf16 v[48:51], v[156:159], v[178:181], v[48:51]
	v_mfma_f32_16x16x32_bf16 v[36:39], v[144:147], v[182:185], v[36:39]
	v_mfma_f32_16x16x32_bf16 v[36:39], v[148:151], v[194:197], v[36:39]
	v_mfma_f32_16x16x32_bf16 v[32:35], v[152:155], v[182:185], v[32:35]
	v_mfma_f32_16x16x32_bf16 v[32:35], v[156:159], v[194:197], v[32:35]
	v_mfma_f32_16x16x32_bf16 v[20:23], v[144:147], v[198:201], v[20:23]
	v_mfma_f32_16x16x32_bf16 v[20:23], v[148:151], v[206:209], v[20:23]
	v_mfma_f32_16x16x32_bf16 v[16:19], v[152:155], v[198:201], v[16:19]
	v_mfma_f32_16x16x32_bf16 v[16:19], v[156:159], v[206:209], v[16:19]
	v_mfma_f32_16x16x32_bf16 v[4:7], v[144:147], v[210:213], v[4:7]
	v_mfma_f32_16x16x32_bf16 v[4:7], v[148:151], v[214:217], v[4:7]
	v_mfma_f32_16x16x32_bf16 v[0:3], v[152:155], v[210:213], v[0:3]
	v_mfma_f32_16x16x32_bf16 v[0:3], v[156:159], v[214:217], v[0:3]
	s_setprio 0
	s_barrier
	s_add_i32 s57, s57, 2
	s_add_u32 s8, s8, 0x100
	s_addc_u32 s9, s9, 0
	s_add_u32 s55, s55, 0x100
	s_addc_u32 s3, s3, 0
	s_cmp_gt_u32 s57, 29
